# out-projection residual epilogue (xout = xin + acc) software-pipelined: xin loads five row-groups ahead, counted vmcnt; all four GEMM_OUT phases (on top of rope pipelining, DPP reductions, attention l
# baseline (speedup 1.0000x reference)
.LBB0_377:
	v_lshl_add_u32 v142, s18, 8, v144
	v_lshl_or_b32 v140, s40, 8, v146
	v_readlane_b32 s52, v255, 7
	v_readlane_b32 s53, v255, 8
	s_nop 2
	s_mov_b64 s[48:49], s[52:53]
	v_readlane_b32 s54, v255, 9
	v_readlane_b32 s55, v255, 10
	v_readlane_b32 s56, v255, 11
	v_readlane_b32 s57, v255, 12
	v_readlane_b32 s58, v255, 13
	v_readlane_b32 s59, v255, 14
	v_readlane_b32 s60, v255, 15
	v_readlane_b32 s61, v255, 16
	v_readlane_b32 s62, v255, 17
	v_readlane_b32 s63, v255, 18
	v_readlane_b32 s64, v255, 19
	v_readlane_b32 s65, v255, 20
	v_readlane_b32 s66, v255, 21
	v_readlane_b32 s67, v255, 22
	s_mov_b64 s[52:53], s[56:57]
	s_andn2_b64 vcc, exec, s[2:3]
	s_mov_b64 s[2:3], -1
	s_mov_b64 s[54:55], s[58:59]
	s_mov_b64 s[56:57], s[60:61]
	s_mov_b64 s[58:59], s[62:63]
	s_mov_b64 s[60:61], s[64:65]
	s_mov_b64 s[62:63], s[66:67]
	v_ashrrev_i32_e32 v141, 31, v140
	v_mov_b32_e32 v246, v142
	v_ashrrev_i32_e32 v247, 31, v246
	v_lshlrev_b64 v[246:247], 11, v[246:247]
	v_lshl_add_u64 v[246:247], v[246:247], 0, v[140:141]
	v_lshlrev_b64 v[246:247], 2, v[246:247]
	v_lshl_add_u64 v[248:249], s[48:49], 0, v[246:247]
	global_load_dwordx4 v[160:163], v[248:249], off
	global_load_dwordx4 v[164:167], v[248:249], off offset:64
	global_load_dwordx4 v[168:171], v[248:249], off offset:512
	global_load_dwordx4 v[172:175], v[248:249], off offset:576
	v_or_b32_e32 v246, 0x10, v142
	v_ashrrev_i32_e32 v247, 31, v246
	v_lshlrev_b64 v[246:247], 11, v[246:247]
	v_lshl_add_u64 v[246:247], v[246:247], 0, v[140:141]
	v_lshlrev_b64 v[246:247], 2, v[246:247]
	v_lshl_add_u64 v[248:249], s[48:49], 0, v[246:247]
	global_load_dwordx4 v[176:179], v[248:249], off
	global_load_dwordx4 v[180:183], v[248:249], off offset:64
	global_load_dwordx4 v[184:187], v[248:249], off offset:512
	global_load_dwordx4 v[188:191], v[248:249], off offset:576
	v_or_b32_e32 v246, 0x20, v142
	v_ashrrev_i32_e32 v247, 31, v246
	v_lshlrev_b64 v[246:247], 11, v[246:247]
	v_lshl_add_u64 v[246:247], v[246:247], 0, v[140:141]
	v_lshlrev_b64 v[246:247], 2, v[246:247]
	v_lshl_add_u64 v[248:249], s[48:49], 0, v[246:247]
	global_load_dwordx4 v[192:195], v[248:249], off
	global_load_dwordx4 v[196:199], v[248:249], off offset:64
	global_load_dwordx4 v[200:203], v[248:249], off offset:512
	global_load_dwordx4 v[204:207], v[248:249], off offset:576
	v_or_b32_e32 v246, 0x30, v142
	v_ashrrev_i32_e32 v247, 31, v246
	v_lshlrev_b64 v[246:247], 11, v[246:247]
	v_lshl_add_u64 v[246:247], v[246:247], 0, v[140:141]
	v_lshlrev_b64 v[246:247], 2, v[246:247]
	v_lshl_add_u64 v[248:249], s[48:49], 0, v[246:247]
	global_load_dwordx4 v[214:217], v[248:249], off
	global_load_dwordx4 v[218:221], v[248:249], off offset:64
	global_load_dwordx4 v[222:225], v[248:249], off offset:512
	global_load_dwordx4 v[226:229], v[248:249], off offset:576
	v_or_b32_e32 v246, 0x80, v142
	v_ashrrev_i32_e32 v247, 31, v246
	v_lshlrev_b64 v[246:247], 11, v[246:247]
	v_lshl_add_u64 v[246:247], v[246:247], 0, v[140:141]
	v_lshlrev_b64 v[246:247], 2, v[246:247]
	v_lshl_add_u64 v[248:249], s[48:49], 0, v[246:247]
	global_load_dwordx4 v[230:233], v[248:249], off
	global_load_dwordx4 v[234:237], v[248:249], off offset:64
	global_load_dwordx4 v[238:241], v[248:249], off offset:512
	global_load_dwordx4 v[242:245], v[248:249], off offset:576
	s_waitcnt vmcnt(16)
	v_pk_add_f32 v[160:161], v[124:125], v[160:161]
	v_pk_add_f32 v[162:163], v[126:127], v[162:163]
	v_pk_add_f32 v[164:165], v[120:121], v[164:165]
	v_pk_add_f32 v[166:167], v[122:123], v[166:167]
	v_pk_add_f32 v[168:169], v[116:117], v[168:169]
	v_pk_add_f32 v[170:171], v[118:119], v[170:171]
	v_pk_add_f32 v[172:173], v[104:105], v[172:173]
	v_pk_add_f32 v[174:175], v[106:107], v[174:175]
	v_mov_b32_e32 v246, v142
	v_ashrrev_i32_e32 v247, 31, v246
	v_lshlrev_b64 v[246:247], 11, v[246:247]
	v_lshl_add_u64 v[246:247], v[246:247], 0, v[140:141]
	v_lshlrev_b64 v[246:247], 2, v[246:247]
	v_lshl_add_u64 v[250:251], s[78:79], 0, v[246:247]
	global_store_dwordx4 v[250:251], v[160:163], off
	global_store_dwordx4 v[250:251], v[164:167], off offset:64
	global_store_dwordx4 v[250:251], v[168:171], off offset:512
	global_store_dwordx4 v[250:251], v[172:175], off offset:576
	v_or_b32_e32 v246, 0x90, v142
	v_ashrrev_i32_e32 v247, 31, v246
	v_lshlrev_b64 v[246:247], 11, v[246:247]
	v_lshl_add_u64 v[246:247], v[246:247], 0, v[140:141]
	v_lshlrev_b64 v[246:247], 2, v[246:247]
	v_lshl_add_u64 v[248:249], s[48:49], 0, v[246:247]
	global_load_dwordx4 v[160:163], v[248:249], off
	global_load_dwordx4 v[164:167], v[248:249], off offset:64
	global_load_dwordx4 v[168:171], v[248:249], off offset:512
	global_load_dwordx4 v[172:175], v[248:249], off offset:576
	s_waitcnt vmcnt(20)
	v_pk_add_f32 v[176:177], v[112:113], v[176:177]
	v_pk_add_f32 v[178:179], v[114:115], v[178:179]
	v_pk_add_f32 v[180:181], v[108:109], v[180:181]
	v_pk_add_f32 v[182:183], v[110:111], v[182:183]
	v_pk_add_f32 v[184:185], v[100:101], v[184:185]
	v_pk_add_f32 v[186:187], v[102:103], v[186:187]
	v_pk_add_f32 v[188:189], v[88:89], v[188:189]
	v_pk_add_f32 v[190:191], v[90:91], v[190:191]
	v_or_b32_e32 v246, 0x10, v142
	v_ashrrev_i32_e32 v247, 31, v246
	v_lshlrev_b64 v[246:247], 11, v[246:247]
	v_lshl_add_u64 v[246:247], v[246:247], 0, v[140:141]
	v_lshlrev_b64 v[246:247], 2, v[246:247]
	v_lshl_add_u64 v[250:251], s[78:79], 0, v[246:247]
	global_store_dwordx4 v[250:251], v[176:179], off
	global_store_dwordx4 v[250:251], v[180:183], off offset:64
	global_store_dwordx4 v[250:251], v[184:187], off offset:512
	global_store_dwordx4 v[250:251], v[188:191], off offset:576
	v_or_b32_e32 v246, 0xa0, v142
	v_ashrrev_i32_e32 v247, 31, v246
	v_lshlrev_b64 v[246:247], 11, v[246:247]
	v_lshl_add_u64 v[246:247], v[246:247], 0, v[140:141]
	v_lshlrev_b64 v[246:247], 2, v[246:247]
	v_lshl_add_u64 v[248:249], s[48:49], 0, v[246:247]
	global_load_dwordx4 v[176:179], v[248:249], off
	global_load_dwordx4 v[180:183], v[248:249], off offset:64
	global_load_dwordx4 v[184:187], v[248:249], off offset:512
	global_load_dwordx4 v[188:191], v[248:249], off offset:576
	s_waitcnt vmcnt(24)
	v_pk_add_f32 v[192:193], v[96:97], v[192:193]
	v_pk_add_f32 v[194:195], v[98:99], v[194:195]
	v_pk_add_f32 v[196:197], v[92:93], v[196:197]
	v_pk_add_f32 v[198:199], v[94:95], v[198:199]
	v_pk_add_f32 v[200:201], v[84:85], v[200:201]
	v_pk_add_f32 v[202:203], v[86:87], v[202:203]
	v_pk_add_f32 v[204:205], v[72:73], v[204:205]
	v_pk_add_f32 v[206:207], v[74:75], v[206:207]
	v_or_b32_e32 v246, 0x20, v142
	v_ashrrev_i32_e32 v247, 31, v246
	v_lshlrev_b64 v[246:247], 11, v[246:247]
	v_lshl_add_u64 v[246:247], v[246:247], 0, v[140:141]
	v_lshlrev_b64 v[246:247], 2, v[246:247]
	v_lshl_add_u64 v[250:251], s[78:79], 0, v[246:247]
	global_store_dwordx4 v[250:251], v[192:195], off
	global_store_dwordx4 v[250:251], v[196:199], off offset:64
	global_store_dwordx4 v[250:251], v[200:203], off offset:512
	global_store_dwordx4 v[250:251], v[204:207], off offset:576
	v_or_b32_e32 v246, 0xb0, v142
	v_ashrrev_i32_e32 v247, 31, v246
	v_lshlrev_b64 v[246:247], 11, v[246:247]
	v_lshl_add_u64 v[246:247], v[246:247], 0, v[140:141]
	v_lshlrev_b64 v[246:247], 2, v[246:247]
	v_lshl_add_u64 v[248:249], s[48:49], 0, v[246:247]
	global_load_dwordx4 v[192:195], v[248:249], off
	global_load_dwordx4 v[196:199], v[248:249], off offset:64
	global_load_dwordx4 v[200:203], v[248:249], off offset:512
	global_load_dwordx4 v[204:207], v[248:249], off offset:576
	s_waitcnt vmcnt(28)
	v_pk_add_f32 v[214:215], v[80:81], v[214:215]
	v_pk_add_f32 v[216:217], v[82:83], v[216:217]
	v_pk_add_f32 v[218:219], v[76:77], v[218:219]
	v_pk_add_f32 v[220:221], v[78:79], v[220:221]
	v_pk_add_f32 v[222:223], v[68:69], v[222:223]
	v_pk_add_f32 v[224:225], v[70:71], v[224:225]
	v_pk_add_f32 v[226:227], v[64:65], v[226:227]
	v_pk_add_f32 v[228:229], v[66:67], v[228:229]
	v_or_b32_e32 v246, 0x30, v142
	v_ashrrev_i32_e32 v247, 31, v246
	v_lshlrev_b64 v[246:247], 11, v[246:247]
	v_lshl_add_u64 v[246:247], v[246:247], 0, v[140:141]
	v_lshlrev_b64 v[246:247], 2, v[246:247]
	v_lshl_add_u64 v[250:251], s[78:79], 0, v[246:247]
	global_store_dwordx4 v[250:251], v[214:217], off
	global_store_dwordx4 v[250:251], v[218:221], off offset:64
	global_store_dwordx4 v[250:251], v[222:225], off offset:512
	global_store_dwordx4 v[250:251], v[226:229], off offset:576
	s_waitcnt vmcnt(28)
	v_pk_add_f32 v[230:231], v[60:61], v[230:231]
	v_pk_add_f32 v[232:233], v[62:63], v[232:233]
	v_pk_add_f32 v[234:235], v[56:57], v[234:235]
	v_pk_add_f32 v[236:237], v[58:59], v[236:237]
	v_pk_add_f32 v[238:239], v[52:53], v[238:239]
	v_pk_add_f32 v[240:241], v[54:55], v[240:241]
	v_pk_add_f32 v[242:243], v[40:41], v[242:243]
	v_pk_add_f32 v[244:245], v[42:43], v[244:245]
	v_or_b32_e32 v246, 0x80, v142
	v_ashrrev_i32_e32 v247, 31, v246
	v_lshlrev_b64 v[246:247], 11, v[246:247]
	v_lshl_add_u64 v[246:247], v[246:247], 0, v[140:141]
	v_lshlrev_b64 v[246:247], 2, v[246:247]
	v_lshl_add_u64 v[250:251], s[78:79], 0, v[246:247]
	global_store_dwordx4 v[250:251], v[230:233], off
	global_store_dwordx4 v[250:251], v[234:237], off offset:64
	global_store_dwordx4 v[250:251], v[238:241], off offset:512
	global_store_dwordx4 v[250:251], v[242:245], off offset:576
	s_waitcnt vmcnt(24)
	v_pk_add_f32 v[160:161], v[48:49], v[160:161]
	v_pk_add_f32 v[162:163], v[50:51], v[162:163]
	v_pk_add_f32 v[164:165], v[44:45], v[164:165]
	v_pk_add_f32 v[166:167], v[46:47], v[166:167]
	v_pk_add_f32 v[168:169], v[36:37], v[168:169]
	v_pk_add_f32 v[170:171], v[38:39], v[170:171]
	v_pk_add_f32 v[172:173], v[24:25], v[172:173]
	v_pk_add_f32 v[174:175], v[26:27], v[174:175]
	v_or_b32_e32 v246, 0x90, v142
	v_ashrrev_i32_e32 v247, 31, v246
	v_lshlrev_b64 v[246:247], 11, v[246:247]
	v_lshl_add_u64 v[246:247], v[246:247], 0, v[140:141]
	v_lshlrev_b64 v[246:247], 2, v[246:247]
	v_lshl_add_u64 v[250:251], s[78:79], 0, v[246:247]
	global_store_dwordx4 v[250:251], v[160:163], off
	global_store_dwordx4 v[250:251], v[164:167], off offset:64
	global_store_dwordx4 v[250:251], v[168:171], off offset:512
	global_store_dwordx4 v[250:251], v[172:175], off offset:576
	s_waitcnt vmcnt(20)
	v_pk_add_f32 v[176:177], v[32:33], v[176:177]
	v_pk_add_f32 v[178:179], v[34:35], v[178:179]
	v_pk_add_f32 v[180:181], v[28:29], v[180:181]
	v_pk_add_f32 v[182:183], v[30:31], v[182:183]
	v_pk_add_f32 v[184:185], v[20:21], v[184:185]
	v_pk_add_f32 v[186:187], v[22:23], v[186:187]
	v_pk_add_f32 v[188:189], v[8:9], v[188:189]
	v_pk_add_f32 v[190:191], v[10:11], v[190:191]
	v_or_b32_e32 v246, 0xa0, v142
	v_ashrrev_i32_e32 v247, 31, v246
	v_lshlrev_b64 v[246:247], 11, v[246:247]
	v_lshl_add_u64 v[246:247], v[246:247], 0, v[140:141]
	v_lshlrev_b64 v[246:247], 2, v[246:247]
	v_lshl_add_u64 v[250:251], s[78:79], 0, v[246:247]
	global_store_dwordx4 v[250:251], v[176:179], off
	global_store_dwordx4 v[250:251], v[180:183], off offset:64
	global_store_dwordx4 v[250:251], v[184:187], off offset:512
	global_store_dwordx4 v[250:251], v[188:191], off offset:576
	s_waitcnt vmcnt(16)
	v_pk_add_f32 v[192:193], v[16:17], v[192:193]
	v_pk_add_f32 v[194:195], v[18:19], v[194:195]
	v_pk_add_f32 v[196:197], v[12:13], v[196:197]
	v_pk_add_f32 v[198:199], v[14:15], v[198:199]
	v_pk_add_f32 v[200:201], v[4:5], v[200:201]
	v_pk_add_f32 v[202:203], v[6:7], v[202:203]
	v_pk_add_f32 v[204:205], v[0:1], v[204:205]
	v_pk_add_f32 v[206:207], v[2:3], v[206:207]
	v_or_b32_e32 v246, 0xb0, v142
	v_ashrrev_i32_e32 v247, 31, v246
	v_lshlrev_b64 v[246:247], 11, v[246:247]
	v_lshl_add_u64 v[246:247], v[246:247], 0, v[140:141]
	v_lshlrev_b64 v[246:247], 2, v[246:247]
	v_lshl_add_u64 v[250:251], s[78:79], 0, v[246:247]
	global_store_dwordx4 v[250:251], v[192:195], off
	global_store_dwordx4 v[250:251], v[196:199], off offset:64
	global_store_dwordx4 v[250:251], v[200:203], off offset:512
	global_store_dwordx4 v[250:251], v[204:207], off offset:576
	s_cbranch_vccnz .LBB0_366
	s_andn2_b64 vcc, exec, s[0:1]
	s_cbranch_vccnz .LBB0_365
	s_barrier
	s_branch .LBB0_365

.LBB0_739:
	v_lshl_add_u32 v142, s18, 8, v144
	v_lshl_or_b32 v140, s40, 8, v146
	s_andn2_b64 vcc, exec, s[2:3]
	s_mov_b64 s[2:3], -1
	v_ashrrev_i32_e32 v141, 31, v140
	v_mov_b32_e32 v246, v142
	v_ashrrev_i32_e32 v247, 31, v246
	v_lshlrev_b64 v[246:247], 11, v[246:247]
	v_lshl_add_u64 v[246:247], v[246:247], 0, v[140:141]
	v_lshlrev_b64 v[246:247], 2, v[246:247]
	v_lshl_add_u64 v[248:249], s[78:79], 0, v[246:247]
	global_load_dwordx4 v[160:163], v[248:249], off
	global_load_dwordx4 v[164:167], v[248:249], off offset:64
	global_load_dwordx4 v[168:171], v[248:249], off offset:512
	global_load_dwordx4 v[172:175], v[248:249], off offset:576
	v_or_b32_e32 v246, 0x10, v142
	v_ashrrev_i32_e32 v247, 31, v246
	v_lshlrev_b64 v[246:247], 11, v[246:247]
	v_lshl_add_u64 v[246:247], v[246:247], 0, v[140:141]
	v_lshlrev_b64 v[246:247], 2, v[246:247]
	v_lshl_add_u64 v[248:249], s[78:79], 0, v[246:247]
	global_load_dwordx4 v[176:179], v[248:249], off
	global_load_dwordx4 v[180:183], v[248:249], off offset:64
	global_load_dwordx4 v[184:187], v[248:249], off offset:512
	global_load_dwordx4 v[188:191], v[248:249], off offset:576
	v_or_b32_e32 v246, 0x20, v142
	v_ashrrev_i32_e32 v247, 31, v246
	v_lshlrev_b64 v[246:247], 11, v[246:247]
	v_lshl_add_u64 v[246:247], v[246:247], 0, v[140:141]
	v_lshlrev_b64 v[246:247], 2, v[246:247]
	v_lshl_add_u64 v[248:249], s[78:79], 0, v[246:247]
	global_load_dwordx4 v[192:195], v[248:249], off
	global_load_dwordx4 v[196:199], v[248:249], off offset:64
	global_load_dwordx4 v[200:203], v[248:249], off offset:512
	global_load_dwordx4 v[204:207], v[248:249], off offset:576
	v_or_b32_e32 v246, 0x30, v142
	v_ashrrev_i32_e32 v247, 31, v246
	v_lshlrev_b64 v[246:247], 11, v[246:247]
	v_lshl_add_u64 v[246:247], v[246:247], 0, v[140:141]
	v_lshlrev_b64 v[246:247], 2, v[246:247]
	v_lshl_add_u64 v[248:249], s[78:79], 0, v[246:247]
	global_load_dwordx4 v[214:217], v[248:249], off
	global_load_dwordx4 v[218:221], v[248:249], off offset:64
	global_load_dwordx4 v[222:225], v[248:249], off offset:512
	global_load_dwordx4 v[226:229], v[248:249], off offset:576
	v_or_b32_e32 v246, 0x80, v142
	v_ashrrev_i32_e32 v247, 31, v246
	v_lshlrev_b64 v[246:247], 11, v[246:247]
	v_lshl_add_u64 v[246:247], v[246:247], 0, v[140:141]
	v_lshlrev_b64 v[246:247], 2, v[246:247]
	v_lshl_add_u64 v[248:249], s[78:79], 0, v[246:247]
	global_load_dwordx4 v[230:233], v[248:249], off
	global_load_dwordx4 v[234:237], v[248:249], off offset:64
	global_load_dwordx4 v[238:241], v[248:249], off offset:512
	global_load_dwordx4 v[242:245], v[248:249], off offset:576
	s_waitcnt vmcnt(16)
	v_pk_add_f32 v[160:161], v[124:125], v[160:161]
	v_pk_add_f32 v[162:163], v[126:127], v[162:163]
	v_pk_add_f32 v[164:165], v[120:121], v[164:165]
	v_pk_add_f32 v[166:167], v[122:123], v[166:167]
	v_pk_add_f32 v[168:169], v[108:109], v[168:169]
	v_pk_add_f32 v[170:171], v[110:111], v[170:171]
	v_pk_add_f32 v[172:173], v[104:105], v[172:173]
	v_pk_add_f32 v[174:175], v[106:107], v[174:175]
	v_mov_b32_e32 v246, v142
	v_ashrrev_i32_e32 v247, 31, v246
	v_lshlrev_b64 v[246:247], 11, v[246:247]
	v_lshl_add_u64 v[246:247], v[246:247], 0, v[140:141]
	v_lshlrev_b64 v[246:247], 2, v[246:247]
	v_lshl_add_u64 v[250:251], s[78:79], 0, v[246:247]
	global_store_dwordx4 v[250:251], v[160:163], off
	global_store_dwordx4 v[250:251], v[164:167], off offset:64
	global_store_dwordx4 v[250:251], v[168:171], off offset:512
	global_store_dwordx4 v[250:251], v[172:175], off offset:576
	v_or_b32_e32 v246, 0x90, v142
	v_ashrrev_i32_e32 v247, 31, v246
	v_lshlrev_b64 v[246:247], 11, v[246:247]
	v_lshl_add_u64 v[246:247], v[246:247], 0, v[140:141]
	v_lshlrev_b64 v[246:247], 2, v[246:247]
	v_lshl_add_u64 v[248:249], s[78:79], 0, v[246:247]
	global_load_dwordx4 v[160:163], v[248:249], off
	global_load_dwordx4 v[164:167], v[248:249], off offset:64
	global_load_dwordx4 v[168:171], v[248:249], off offset:512
	global_load_dwordx4 v[172:175], v[248:249], off offset:576
	s_waitcnt vmcnt(20)
	v_pk_add_f32 v[176:177], v[116:117], v[176:177]
	v_pk_add_f32 v[178:179], v[118:119], v[178:179]
	v_pk_add_f32 v[180:181], v[112:113], v[180:181]
	v_pk_add_f32 v[182:183], v[114:115], v[182:183]
	v_pk_add_f32 v[184:185], v[100:101], v[184:185]
	v_pk_add_f32 v[186:187], v[102:103], v[186:187]
	v_pk_add_f32 v[188:189], v[96:97], v[188:189]
	v_pk_add_f32 v[190:191], v[98:99], v[190:191]
	v_or_b32_e32 v246, 0x10, v142
	v_ashrrev_i32_e32 v247, 31, v246
	v_lshlrev_b64 v[246:247], 11, v[246:247]
	v_lshl_add_u64 v[246:247], v[246:247], 0, v[140:141]
	v_lshlrev_b64 v[246:247], 2, v[246:247]
	v_lshl_add_u64 v[250:251], s[78:79], 0, v[246:247]
	global_store_dwordx4 v[250:251], v[176:179], off
	global_store_dwordx4 v[250:251], v[180:183], off offset:64
	global_store_dwordx4 v[250:251], v[184:187], off offset:512
	global_store_dwordx4 v[250:251], v[188:191], off offset:576
	v_or_b32_e32 v246, 0xa0, v142
	v_ashrrev_i32_e32 v247, 31, v246
	v_lshlrev_b64 v[246:247], 11, v[246:247]
	v_lshl_add_u64 v[246:247], v[246:247], 0, v[140:141]
	v_lshlrev_b64 v[246:247], 2, v[246:247]
	v_lshl_add_u64 v[248:249], s[78:79], 0, v[246:247]
	global_load_dwordx4 v[176:179], v[248:249], off
	global_load_dwordx4 v[180:183], v[248:249], off offset:64
	global_load_dwordx4 v[184:187], v[248:249], off offset:512
	global_load_dwordx4 v[188:191], v[248:249], off offset:576
	s_waitcnt vmcnt(24)
	v_pk_add_f32 v[192:193], v[92:93], v[192:193]
	v_pk_add_f32 v[194:195], v[94:95], v[194:195]
	v_pk_add_f32 v[196:197], v[88:89], v[196:197]
	v_pk_add_f32 v[198:199], v[90:91], v[198:199]
	v_pk_add_f32 v[200:201], v[76:77], v[200:201]
	v_pk_add_f32 v[202:203], v[78:79], v[202:203]
	v_pk_add_f32 v[204:205], v[72:73], v[204:205]
	v_pk_add_f32 v[206:207], v[74:75], v[206:207]
	v_or_b32_e32 v246, 0x20, v142
	v_ashrrev_i32_e32 v247, 31, v246
	v_lshlrev_b64 v[246:247], 11, v[246:247]
	v_lshl_add_u64 v[246:247], v[246:247], 0, v[140:141]
	v_lshlrev_b64 v[246:247], 2, v[246:247]
	v_lshl_add_u64 v[250:251], s[78:79], 0, v[246:247]
	global_store_dwordx4 v[250:251], v[192:195], off
	global_store_dwordx4 v[250:251], v[196:199], off offset:64
	global_store_dwordx4 v[250:251], v[200:203], off offset:512
	global_store_dwordx4 v[250:251], v[204:207], off offset:576
	v_or_b32_e32 v246, 0xb0, v142
	v_ashrrev_i32_e32 v247, 31, v246
	v_lshlrev_b64 v[246:247], 11, v[246:247]
	v_lshl_add_u64 v[246:247], v[246:247], 0, v[140:141]
	v_lshlrev_b64 v[246:247], 2, v[246:247]
	v_lshl_add_u64 v[248:249], s[78:79], 0, v[246:247]
	global_load_dwordx4 v[192:195], v[248:249], off
	global_load_dwordx4 v[196:199], v[248:249], off offset:64
	global_load_dwordx4 v[200:203], v[248:249], off offset:512
	global_load_dwordx4 v[204:207], v[248:249], off offset:576
	s_waitcnt vmcnt(28)
	v_pk_add_f32 v[214:215], v[84:85], v[214:215]
	v_pk_add_f32 v[216:217], v[86:87], v[216:217]
	v_pk_add_f32 v[218:219], v[80:81], v[218:219]
	v_pk_add_f32 v[220:221], v[82:83], v[220:221]
	v_pk_add_f32 v[222:223], v[68:69], v[222:223]
	v_pk_add_f32 v[224:225], v[70:71], v[224:225]
	v_pk_add_f32 v[226:227], v[64:65], v[226:227]
	v_pk_add_f32 v[228:229], v[66:67], v[228:229]
	v_or_b32_e32 v246, 0x30, v142
	v_ashrrev_i32_e32 v247, 31, v246
	v_lshlrev_b64 v[246:247], 11, v[246:247]
	v_lshl_add_u64 v[246:247], v[246:247], 0, v[140:141]
	v_lshlrev_b64 v[246:247], 2, v[246:247]
	v_lshl_add_u64 v[250:251], s[78:79], 0, v[246:247]
	global_store_dwordx4 v[250:251], v[214:217], off
	global_store_dwordx4 v[250:251], v[218:221], off offset:64
	global_store_dwordx4 v[250:251], v[222:225], off offset:512
	global_store_dwordx4 v[250:251], v[226:229], off offset:576
	s_waitcnt vmcnt(28)
	v_pk_add_f32 v[230:231], v[60:61], v[230:231]
	v_pk_add_f32 v[232:233], v[62:63], v[232:233]
	v_pk_add_f32 v[234:235], v[56:57], v[234:235]
	v_pk_add_f32 v[236:237], v[58:59], v[236:237]
	v_pk_add_f32 v[238:239], v[44:45], v[238:239]
	v_pk_add_f32 v[240:241], v[46:47], v[240:241]
	v_pk_add_f32 v[242:243], v[40:41], v[242:243]
	v_pk_add_f32 v[244:245], v[42:43], v[244:245]
	v_or_b32_e32 v246, 0x80, v142
	v_ashrrev_i32_e32 v247, 31, v246
	v_lshlrev_b64 v[246:247], 11, v[246:247]
	v_lshl_add_u64 v[246:247], v[246:247], 0, v[140:141]
	v_lshlrev_b64 v[246:247], 2, v[246:247]
	v_lshl_add_u64 v[250:251], s[78:79], 0, v[246:247]
	global_store_dwordx4 v[250:251], v[230:233], off
	global_store_dwordx4 v[250:251], v[234:237], off offset:64
	global_store_dwordx4 v[250:251], v[238:241], off offset:512
	global_store_dwordx4 v[250:251], v[242:245], off offset:576
	s_waitcnt vmcnt(24)
	v_pk_add_f32 v[160:161], v[52:53], v[160:161]
	v_pk_add_f32 v[162:163], v[54:55], v[162:163]
	v_pk_add_f32 v[164:165], v[48:49], v[164:165]
	v_pk_add_f32 v[166:167], v[50:51], v[166:167]
	v_pk_add_f32 v[168:169], v[36:37], v[168:169]
	v_pk_add_f32 v[170:171], v[38:39], v[170:171]
	v_pk_add_f32 v[172:173], v[32:33], v[172:173]
	v_pk_add_f32 v[174:175], v[34:35], v[174:175]
	v_or_b32_e32 v246, 0x90, v142
	v_ashrrev_i32_e32 v247, 31, v246
	v_lshlrev_b64 v[246:247], 11, v[246:247]
	v_lshl_add_u64 v[246:247], v[246:247], 0, v[140:141]
	v_lshlrev_b64 v[246:247], 2, v[246:247]
	v_lshl_add_u64 v[250:251], s[78:79], 0, v[246:247]
	global_store_dwordx4 v[250:251], v[160:163], off
	global_store_dwordx4 v[250:251], v[164:167], off offset:64
	global_store_dwordx4 v[250:251], v[168:171], off offset:512
	global_store_dwordx4 v[250:251], v[172:175], off offset:576
	s_waitcnt vmcnt(20)
	v_pk_add_f32 v[176:177], v[28:29], v[176:177]
	v_pk_add_f32 v[178:179], v[30:31], v[178:179]
	v_pk_add_f32 v[180:181], v[24:25], v[180:181]
	v_pk_add_f32 v[182:183], v[26:27], v[182:183]
	v_pk_add_f32 v[184:185], v[12:13], v[184:185]
	v_pk_add_f32 v[186:187], v[14:15], v[186:187]
	v_pk_add_f32 v[188:189], v[8:9], v[188:189]
	v_pk_add_f32 v[190:191], v[10:11], v[190:191]
	v_or_b32_e32 v246, 0xa0, v142
	v_ashrrev_i32_e32 v247, 31, v246
	v_lshlrev_b64 v[246:247], 11, v[246:247]
	v_lshl_add_u64 v[246:247], v[246:247], 0, v[140:141]
	v_lshlrev_b64 v[246:247], 2, v[246:247]
	v_lshl_add_u64 v[250:251], s[78:79], 0, v[246:247]
	global_store_dwordx4 v[250:251], v[176:179], off
	global_store_dwordx4 v[250:251], v[180:183], off offset:64
	global_store_dwordx4 v[250:251], v[184:187], off offset:512
	global_store_dwordx4 v[250:251], v[188:191], off offset:576
	s_waitcnt vmcnt(16)
	v_pk_add_f32 v[192:193], v[20:21], v[192:193]
	v_pk_add_f32 v[194:195], v[22:23], v[194:195]
	v_pk_add_f32 v[196:197], v[16:17], v[196:197]
	v_pk_add_f32 v[198:199], v[18:19], v[198:199]
	v_pk_add_f32 v[200:201], v[4:5], v[200:201]
	v_pk_add_f32 v[202:203], v[6:7], v[202:203]
	v_pk_add_f32 v[204:205], v[0:1], v[204:205]
	v_pk_add_f32 v[206:207], v[2:3], v[206:207]
	v_or_b32_e32 v246, 0xb0, v142
	v_ashrrev_i32_e32 v247, 31, v246
	v_lshlrev_b64 v[246:247], 11, v[246:247]
	v_lshl_add_u64 v[246:247], v[246:247], 0, v[140:141]
	v_lshlrev_b64 v[246:247], 2, v[246:247]
	v_lshl_add_u64 v[250:251], s[78:79], 0, v[246:247]
	global_store_dwordx4 v[250:251], v[192:195], off
	global_store_dwordx4 v[250:251], v[196:199], off offset:64
	global_store_dwordx4 v[250:251], v[200:203], off offset:512
	global_store_dwordx4 v[250:251], v[204:207], off offset:576
	s_cbranch_vccnz .LBB0_728
	s_andn2_b64 vcc, exec, s[0:1]
	s_cbranch_vccnz .LBB0_727
	s_barrier
	s_branch .LBB0_727

.LBB0_1347:
	v_lshl_add_u32 v142, s16, 8, v144
	v_lshl_or_b32 v140, s39, 8, v146
	s_andn2_b64 vcc, exec, s[2:3]
	s_mov_b64 s[2:3], -1
	v_ashrrev_i32_e32 v141, 31, v140
	v_mov_b32_e32 v246, v142
	v_ashrrev_i32_e32 v247, 31, v246
	v_lshlrev_b64 v[246:247], 11, v[246:247]
	v_lshl_add_u64 v[246:247], v[246:247], 0, v[140:141]
	v_lshlrev_b64 v[246:247], 2, v[246:247]
	v_lshl_add_u64 v[248:249], s[78:79], 0, v[246:247]
	global_load_dwordx4 v[160:163], v[248:249], off
	global_load_dwordx4 v[164:167], v[248:249], off offset:64
	global_load_dwordx4 v[168:171], v[248:249], off offset:512
	global_load_dwordx4 v[172:175], v[248:249], off offset:576
	v_or_b32_e32 v246, 0x10, v142
	v_ashrrev_i32_e32 v247, 31, v246
	v_lshlrev_b64 v[246:247], 11, v[246:247]
	v_lshl_add_u64 v[246:247], v[246:247], 0, v[140:141]
	v_lshlrev_b64 v[246:247], 2, v[246:247]
	v_lshl_add_u64 v[248:249], s[78:79], 0, v[246:247]
	global_load_dwordx4 v[176:179], v[248:249], off
	global_load_dwordx4 v[180:183], v[248:249], off offset:64
	global_load_dwordx4 v[184:187], v[248:249], off offset:512
	global_load_dwordx4 v[188:191], v[248:249], off offset:576
	v_or_b32_e32 v246, 0x20, v142
	v_ashrrev_i32_e32 v247, 31, v246
	v_lshlrev_b64 v[246:247], 11, v[246:247]
	v_lshl_add_u64 v[246:247], v[246:247], 0, v[140:141]
	v_lshlrev_b64 v[246:247], 2, v[246:247]
	v_lshl_add_u64 v[248:249], s[78:79], 0, v[246:247]
	global_load_dwordx4 v[192:195], v[248:249], off
	global_load_dwordx4 v[196:199], v[248:249], off offset:64
	global_load_dwordx4 v[200:203], v[248:249], off offset:512
	global_load_dwordx4 v[204:207], v[248:249], off offset:576
	v_or_b32_e32 v246, 0x30, v142
	v_ashrrev_i32_e32 v247, 31, v246
	v_lshlrev_b64 v[246:247], 11, v[246:247]
	v_lshl_add_u64 v[246:247], v[246:247], 0, v[140:141]
	v_lshlrev_b64 v[246:247], 2, v[246:247]
	v_lshl_add_u64 v[248:249], s[78:79], 0, v[246:247]
	global_load_dwordx4 v[214:217], v[248:249], off
	global_load_dwordx4 v[218:221], v[248:249], off offset:64
	global_load_dwordx4 v[222:225], v[248:249], off offset:512
	global_load_dwordx4 v[226:229], v[248:249], off offset:576
	v_or_b32_e32 v246, 0x80, v142
	v_ashrrev_i32_e32 v247, 31, v246
	v_lshlrev_b64 v[246:247], 11, v[246:247]
	v_lshl_add_u64 v[246:247], v[246:247], 0, v[140:141]
	v_lshlrev_b64 v[246:247], 2, v[246:247]
	v_lshl_add_u64 v[248:249], s[78:79], 0, v[246:247]
	global_load_dwordx4 v[230:233], v[248:249], off
	global_load_dwordx4 v[234:237], v[248:249], off offset:64
	global_load_dwordx4 v[238:241], v[248:249], off offset:512
	global_load_dwordx4 v[242:245], v[248:249], off offset:576
	s_waitcnt vmcnt(16)
	v_pk_add_f32 v[160:161], v[124:125], v[160:161]
	v_pk_add_f32 v[162:163], v[126:127], v[162:163]
	v_pk_add_f32 v[164:165], v[120:121], v[164:165]
	v_pk_add_f32 v[166:167], v[122:123], v[166:167]
	v_pk_add_f32 v[168:169], v[108:109], v[168:169]
	v_pk_add_f32 v[170:171], v[110:111], v[170:171]
	v_pk_add_f32 v[172:173], v[104:105], v[172:173]
	v_pk_add_f32 v[174:175], v[106:107], v[174:175]
	v_mov_b32_e32 v246, v142
	v_ashrrev_i32_e32 v247, 31, v246
	v_lshlrev_b64 v[246:247], 11, v[246:247]
	v_lshl_add_u64 v[246:247], v[246:247], 0, v[140:141]
	v_lshlrev_b64 v[246:247], 2, v[246:247]
	v_lshl_add_u64 v[250:251], s[78:79], 0, v[246:247]
	global_store_dwordx4 v[250:251], v[160:163], off
	global_store_dwordx4 v[250:251], v[164:167], off offset:64
	global_store_dwordx4 v[250:251], v[168:171], off offset:512
	global_store_dwordx4 v[250:251], v[172:175], off offset:576
	v_or_b32_e32 v246, 0x90, v142
	v_ashrrev_i32_e32 v247, 31, v246
	v_lshlrev_b64 v[246:247], 11, v[246:247]
	v_lshl_add_u64 v[246:247], v[246:247], 0, v[140:141]
	v_lshlrev_b64 v[246:247], 2, v[246:247]
	v_lshl_add_u64 v[248:249], s[78:79], 0, v[246:247]
	global_load_dwordx4 v[160:163], v[248:249], off
	global_load_dwordx4 v[164:167], v[248:249], off offset:64
	global_load_dwordx4 v[168:171], v[248:249], off offset:512
	global_load_dwordx4 v[172:175], v[248:249], off offset:576
	s_waitcnt vmcnt(20)
	v_pk_add_f32 v[176:177], v[116:117], v[176:177]
	v_pk_add_f32 v[178:179], v[118:119], v[178:179]
	v_pk_add_f32 v[180:181], v[112:113], v[180:181]
	v_pk_add_f32 v[182:183], v[114:115], v[182:183]
	v_pk_add_f32 v[184:185], v[100:101], v[184:185]
	v_pk_add_f32 v[186:187], v[102:103], v[186:187]
	v_pk_add_f32 v[188:189], v[96:97], v[188:189]
	v_pk_add_f32 v[190:191], v[98:99], v[190:191]
	v_or_b32_e32 v246, 0x10, v142
	v_ashrrev_i32_e32 v247, 31, v246
	v_lshlrev_b64 v[246:247], 11, v[246:247]
	v_lshl_add_u64 v[246:247], v[246:247], 0, v[140:141]
	v_lshlrev_b64 v[246:247], 2, v[246:247]
	v_lshl_add_u64 v[250:251], s[78:79], 0, v[246:247]
	global_store_dwordx4 v[250:251], v[176:179], off
	global_store_dwordx4 v[250:251], v[180:183], off offset:64
	global_store_dwordx4 v[250:251], v[184:187], off offset:512
	global_store_dwordx4 v[250:251], v[188:191], off offset:576
	v_or_b32_e32 v246, 0xa0, v142
	v_ashrrev_i32_e32 v247, 31, v246
	v_lshlrev_b64 v[246:247], 11, v[246:247]
	v_lshl_add_u64 v[246:247], v[246:247], 0, v[140:141]
	v_lshlrev_b64 v[246:247], 2, v[246:247]
	v_lshl_add_u64 v[248:249], s[78:79], 0, v[246:247]
	global_load_dwordx4 v[176:179], v[248:249], off
	global_load_dwordx4 v[180:183], v[248:249], off offset:64
	global_load_dwordx4 v[184:187], v[248:249], off offset:512
	global_load_dwordx4 v[188:191], v[248:249], off offset:576
	s_waitcnt vmcnt(24)
	v_pk_add_f32 v[192:193], v[92:93], v[192:193]
	v_pk_add_f32 v[194:195], v[94:95], v[194:195]
	v_pk_add_f32 v[196:197], v[88:89], v[196:197]
	v_pk_add_f32 v[198:199], v[90:91], v[198:199]
	v_pk_add_f32 v[200:201], v[76:77], v[200:201]
	v_pk_add_f32 v[202:203], v[78:79], v[202:203]
	v_pk_add_f32 v[204:205], v[72:73], v[204:205]
	v_pk_add_f32 v[206:207], v[74:75], v[206:207]
	v_or_b32_e32 v246, 0x20, v142
	v_ashrrev_i32_e32 v247, 31, v246
	v_lshlrev_b64 v[246:247], 11, v[246:247]
	v_lshl_add_u64 v[246:247], v[246:247], 0, v[140:141]
	v_lshlrev_b64 v[246:247], 2, v[246:247]
	v_lshl_add_u64 v[250:251], s[78:79], 0, v[246:247]
	global_store_dwordx4 v[250:251], v[192:195], off
	global_store_dwordx4 v[250:251], v[196:199], off offset:64
	global_store_dwordx4 v[250:251], v[200:203], off offset:512
	global_store_dwordx4 v[250:251], v[204:207], off offset:576
	v_or_b32_e32 v246, 0xb0, v142
	v_ashrrev_i32_e32 v247, 31, v246
	v_lshlrev_b64 v[246:247], 11, v[246:247]
	v_lshl_add_u64 v[246:247], v[246:247], 0, v[140:141]
	v_lshlrev_b64 v[246:247], 2, v[246:247]
	v_lshl_add_u64 v[248:249], s[78:79], 0, v[246:247]
	global_load_dwordx4 v[192:195], v[248:249], off
	global_load_dwordx4 v[196:199], v[248:249], off offset:64
	global_load_dwordx4 v[200:203], v[248:249], off offset:512
	global_load_dwordx4 v[204:207], v[248:249], off offset:576
	s_waitcnt vmcnt(28)
	v_pk_add_f32 v[214:215], v[84:85], v[214:215]
	v_pk_add_f32 v[216:217], v[86:87], v[216:217]
	v_pk_add_f32 v[218:219], v[80:81], v[218:219]
	v_pk_add_f32 v[220:221], v[82:83], v[220:221]
	v_pk_add_f32 v[222:223], v[68:69], v[222:223]
	v_pk_add_f32 v[224:225], v[70:71], v[224:225]
	v_pk_add_f32 v[226:227], v[64:65], v[226:227]
	v_pk_add_f32 v[228:229], v[66:67], v[228:229]
	v_or_b32_e32 v246, 0x30, v142
	v_ashrrev_i32_e32 v247, 31, v246
	v_lshlrev_b64 v[246:247], 11, v[246:247]
	v_lshl_add_u64 v[246:247], v[246:247], 0, v[140:141]
	v_lshlrev_b64 v[246:247], 2, v[246:247]
	v_lshl_add_u64 v[250:251], s[78:79], 0, v[246:247]
	global_store_dwordx4 v[250:251], v[214:217], off
	global_store_dwordx4 v[250:251], v[218:221], off offset:64
	global_store_dwordx4 v[250:251], v[222:225], off offset:512
	global_store_dwordx4 v[250:251], v[226:229], off offset:576
	s_waitcnt vmcnt(28)
	v_pk_add_f32 v[230:231], v[60:61], v[230:231]
	v_pk_add_f32 v[232:233], v[62:63], v[232:233]
	v_pk_add_f32 v[234:235], v[56:57], v[234:235]
	v_pk_add_f32 v[236:237], v[58:59], v[236:237]
	v_pk_add_f32 v[238:239], v[44:45], v[238:239]
	v_pk_add_f32 v[240:241], v[46:47], v[240:241]
	v_pk_add_f32 v[242:243], v[40:41], v[242:243]
	v_pk_add_f32 v[244:245], v[42:43], v[244:245]
	v_or_b32_e32 v246, 0x80, v142
	v_ashrrev_i32_e32 v247, 31, v246
	v_lshlrev_b64 v[246:247], 11, v[246:247]
	v_lshl_add_u64 v[246:247], v[246:247], 0, v[140:141]
	v_lshlrev_b64 v[246:247], 2, v[246:247]
	v_lshl_add_u64 v[250:251], s[78:79], 0, v[246:247]
	global_store_dwordx4 v[250:251], v[230:233], off
	global_store_dwordx4 v[250:251], v[234:237], off offset:64
	global_store_dwordx4 v[250:251], v[238:241], off offset:512
	global_store_dwordx4 v[250:251], v[242:245], off offset:576
	s_waitcnt vmcnt(24)
	v_pk_add_f32 v[160:161], v[52:53], v[160:161]
	v_pk_add_f32 v[162:163], v[54:55], v[162:163]
	v_pk_add_f32 v[164:165], v[48:49], v[164:165]
	v_pk_add_f32 v[166:167], v[50:51], v[166:167]
	v_pk_add_f32 v[168:169], v[36:37], v[168:169]
	v_pk_add_f32 v[170:171], v[38:39], v[170:171]
	v_pk_add_f32 v[172:173], v[32:33], v[172:173]
	v_pk_add_f32 v[174:175], v[34:35], v[174:175]
	v_or_b32_e32 v246, 0x90, v142
	v_ashrrev_i32_e32 v247, 31, v246
	v_lshlrev_b64 v[246:247], 11, v[246:247]
	v_lshl_add_u64 v[246:247], v[246:247], 0, v[140:141]
	v_lshlrev_b64 v[246:247], 2, v[246:247]
	v_lshl_add_u64 v[250:251], s[78:79], 0, v[246:247]
	global_store_dwordx4 v[250:251], v[160:163], off
	global_store_dwordx4 v[250:251], v[164:167], off offset:64
	global_store_dwordx4 v[250:251], v[168:171], off offset:512
	global_store_dwordx4 v[250:251], v[172:175], off offset:576
	s_waitcnt vmcnt(20)
	v_pk_add_f32 v[176:177], v[28:29], v[176:177]
	v_pk_add_f32 v[178:179], v[30:31], v[178:179]
	v_pk_add_f32 v[180:181], v[24:25], v[180:181]
	v_pk_add_f32 v[182:183], v[26:27], v[182:183]
	v_pk_add_f32 v[184:185], v[12:13], v[184:185]
	v_pk_add_f32 v[186:187], v[14:15], v[186:187]
	v_pk_add_f32 v[188:189], v[8:9], v[188:189]
	v_pk_add_f32 v[190:191], v[10:11], v[190:191]
	v_or_b32_e32 v246, 0xa0, v142
	v_ashrrev_i32_e32 v247, 31, v246
	v_lshlrev_b64 v[246:247], 11, v[246:247]
	v_lshl_add_u64 v[246:247], v[246:247], 0, v[140:141]
	v_lshlrev_b64 v[246:247], 2, v[246:247]
	v_lshl_add_u64 v[250:251], s[78:79], 0, v[246:247]
	global_store_dwordx4 v[250:251], v[176:179], off
	global_store_dwordx4 v[250:251], v[180:183], off offset:64
	global_store_dwordx4 v[250:251], v[184:187], off offset:512
	global_store_dwordx4 v[250:251], v[188:191], off offset:576
	s_waitcnt vmcnt(16)
	v_pk_add_f32 v[192:193], v[20:21], v[192:193]
	v_pk_add_f32 v[194:195], v[22:23], v[194:195]
	v_pk_add_f32 v[196:197], v[16:17], v[196:197]
	v_pk_add_f32 v[198:199], v[18:19], v[198:199]
	v_pk_add_f32 v[200:201], v[4:5], v[200:201]
	v_pk_add_f32 v[202:203], v[6:7], v[202:203]
	v_pk_add_f32 v[204:205], v[0:1], v[204:205]
	v_pk_add_f32 v[206:207], v[2:3], v[206:207]
	v_or_b32_e32 v246, 0xb0, v142
	v_ashrrev_i32_e32 v247, 31, v246
	v_lshlrev_b64 v[246:247], 11, v[246:247]
	v_lshl_add_u64 v[246:247], v[246:247], 0, v[140:141]
	v_lshlrev_b64 v[246:247], 2, v[246:247]
	v_lshl_add_u64 v[250:251], s[78:79], 0, v[246:247]
	global_store_dwordx4 v[250:251], v[192:195], off
	global_store_dwordx4 v[250:251], v[196:199], off offset:64
	global_store_dwordx4 v[250:251], v[200:203], off offset:512
	global_store_dwordx4 v[250:251], v[204:207], off offset:576
	s_cbranch_vccnz .LBB0_1336
	s_andn2_b64 vcc, exec, s[0:1]
	s_cbranch_vccnz .LBB0_1335
	s_barrier
	s_branch .LBB0_1335
